# NSA interior tiles: MFMA A-rows of QK permuted (key bits 2,3 swapped) so V^T fragments are conflict-free ds_read_b128 instead of 2-way-conflicting ds_read2_b64
# speedup vs baseline: 1.0069x; 1.0057x over previous
.LBB0_281:
	s_or_b64 exec, exec, s[4:5]
	s_waitcnt vmcnt(0)
	v_mul_f32_e32 v34, 0xbfb8aa3b, v116
	v_exp_f32_e32 v34, v34
	v_or_b32_e32 v0, v41, v43
	v_bitop3_b16 v0, v0, v47, v46 bitop3:0xfe
	v_bitop3_b16 v0, v0, v44, v42 bitop3:0xfe
	v_add_f32_e32 v34, 1.0, v34
	v_div_scale_f32 v35, s[4:5], v34, v34, 1.0
	v_rcp_f32_e32 v36, v35
	v_bitop3_b16 v0, v0, v40, v38 bitop3:0xfe
	v_lshlrev_b32_e32 v121, 2, v60
	v_add_u32_e32 v125, 0x10000, v121
	v_fma_f32 v37, -v35, v36, 1.0
	v_fmac_f32_e32 v36, v37, v36
	v_div_scale_f32 v37, vcc, 1.0, v34, 1.0
	v_mul_f32_e32 v39, v37, v36
	v_fma_f32 v41, -v35, v39, v37
	v_fmac_f32_e32 v39, v41, v36
	v_fma_f32 v35, -v35, v39, v37
	v_div_fmas_f32 v35, v35, v36, v39
	v_div_fixup_f32 v34, v35, v34, 1.0
	v_add_u32_e32 v35, 0x13280, v60
	ds_write_b8 v35, v0
	v_lshl_add_u32 v0, v61, 3, v205
	s_waitcnt lgkmcnt(0)
	s_barrier
	ds_read_b64 v[128:129], v0
	v_mul_f32_e32 v0, v34, v2
	v_mul_f32_e32 v3, v34, v3
	v_mul_f32_e32 v2, v34, v18
	ds_write2st64_b32 v121, v0, v3 offset0:144 offset1:148
	v_mul_f32_e32 v0, v34, v19
	ds_write2st64_b32 v121, v2, v0 offset0:208 offset1:212
	v_mul_f32_e32 v0, v34, v4
	v_mul_f32_e32 v3, v34, v5
	v_mul_f32_e32 v2, v34, v20
	ds_write2st64_b32 v121, v0, v3 offset0:152 offset1:156
	v_mul_f32_e32 v0, v34, v21
	ds_write2st64_b32 v121, v2, v0 offset0:216 offset1:220
	v_mul_f32_e32 v0, v34, v6
	v_mul_f32_e32 v3, v34, v7
	v_mul_f32_e32 v2, v34, v22
	ds_write2st64_b32 v121, v0, v3 offset0:160 offset1:164
	v_mul_f32_e32 v0, v34, v23
	ds_write2st64_b32 v121, v2, v0 offset0:224 offset1:228
	v_mul_f32_e32 v0, v34, v8
	v_mul_f32_e32 v3, v34, v9
	v_mul_f32_e32 v2, v34, v24
	ds_write2st64_b32 v121, v0, v3 offset0:168 offset1:172
	v_mul_f32_e32 v0, v34, v25
	ds_write2st64_b32 v121, v2, v0 offset0:232 offset1:236
	v_mul_f32_e32 v0, v34, v10
	v_mul_f32_e32 v3, v34, v11
	v_mul_f32_e32 v2, v34, v26
	ds_write2st64_b32 v121, v0, v3 offset0:176 offset1:180
	v_mul_f32_e32 v0, v34, v27
	ds_write2st64_b32 v121, v2, v0 offset0:240 offset1:244
	v_mul_f32_e32 v0, v34, v12
	v_mul_f32_e32 v3, v34, v13
	v_mul_f32_e32 v2, v34, v28
	ds_write2st64_b32 v121, v0, v3 offset0:184 offset1:188
	v_mul_f32_e32 v0, v34, v29
	ds_write2st64_b32 v121, v2, v0 offset0:248 offset1:252
	v_mul_f32_e32 v2, v34, v30
	v_mul_f32_e32 v0, v34, v14
	ds_write_b32 v125, v2
	v_mul_f32_e32 v2, v34, v15
	ds_write2st64_b32 v121, v0, v2 offset0:192 offset1:196
	v_mul_f32_e32 v0, v34, v31
	v_add_u32_e32 v127, 0x10400, v121
	v_mul_f32_e32 v2, v34, v32
	v_add_u32_e32 v135, 0x10800, v121
	ds_write_b32 v127, v0
	v_mul_f32_e32 v0, v34, v16
	ds_write_b32 v135, v2
	v_mul_f32_e32 v2, v34, v17
	s_or_b32 s11, s12, s11
	ds_write2st64_b32 v121, v0, v2 offset0:200 offset1:204
	v_mul_f32_e32 v0, v34, v33
	v_add_u32_e32 v152, 0x10c00, v121
	v_mov_b32_e32 v2, v133
	ds_write_b32 v152, v0
	s_lshl_b32 s6, s11, 19
	v_readlane_b32 s4, v253, 25
	s_add_u32 s4, s4, s6
	v_ashrrev_i32_e32 v158, 3, v2
	v_add_u32_e32 v0, 0x100, v2
	v_readlane_b32 s5, v253, 26
	v_ashrrev_i32_e32 v160, 3, v0
	v_ashrrev_i32_e32 v159, 31, v158
	v_lshlrev_b32_e32 v0, 3, v2
	s_addc_u32 s5, s5, 0
	v_readlane_b32 s7, v253, 27
	v_lshlrev_b64 v[4:5], 7, v[158:159]
	v_and_b32_e32 v20, 56, v0
	v_ashrrev_i32_e32 v161, 31, v160
	s_add_u32 s6, s7, s6
	v_readlane_b32 s7, v253, 28
	v_lshl_add_u64 v[4:5], s[4:5], 0, v[4:5]
	v_lshlrev_b32_e32 v0, 1, v20
	v_lshlrev_b64 v[8:9], 7, v[160:161]
	s_addc_u32 s7, s7, 0
	v_lshl_add_u64 v[4:5], v[4:5], 0, v[0:1]
	v_lshl_add_u64 v[8:9], s[4:5], 0, v[8:9]
	v_lshlrev_b64 v[12:13], 13, v[158:159]
	global_load_dwordx4 v[4:7], v[4:5], off
	v_lshl_add_u64 v[8:9], v[8:9], 0, v[0:1]
	v_lshl_add_u64 v[12:13], s[6:7], 0, v[12:13]
	v_lshlrev_b64 v[16:17], 13, v[160:161]
	global_load_dwordx4 v[8:11], v[8:9], off
	v_lshl_add_u64 v[162:163], v[12:13], 0, v[0:1]
	v_lshl_add_u64 v[16:17], s[6:7], 0, v[16:17]
	global_load_dwordx4 v[12:15], v[162:163], off
	v_lshl_add_u64 v[164:165], v[16:17], 0, v[0:1]
	global_load_dwordx4 v[16:19], v[164:165], off
	v_mad_u64_u32 v[166:167], s[6:7], v158, s21, v[20:21]
	v_lshlrev_b32_e32 v3, 1, v166
	v_mad_u64_u32 v[168:169], s[6:7], v160, s21, v[20:21]
	s_waitcnt lgkmcnt(0)
	s_barrier
	s_mov_b32 s12, 0
	s_cmp_lt_i32 s10, 0
	s_waitcnt vmcnt(3)
	ds_write_b128 v3, v[4:7]
	v_lshlrev_b32_e32 v4, 1, v168
	s_waitcnt vmcnt(2)
	ds_write_b128 v4, v[8:11]
	s_waitcnt vmcnt(1)
	ds_write_b128 v3, v[12:15] offset:9216
	s_waitcnt vmcnt(0)
	ds_write_b128 v4, v[16:19] offset:9216
	s_waitcnt lgkmcnt(0)
	s_barrier
	s_cbranch_scc1 .LBB0_298
	v_lshl_add_u64 v[170:171], s[4:5], 0, v[0:1]
	v_bfe_u32 v0, v2, 5, 1
	v_and_b32_e32 v116, 31, v2
	v_lshlrev_b32_e32 v131, 4, v0
	v_lshlrev_b32_e32 v2, 2, v0
	v_lshlrev_b32_e32 v0, 3, v0
	v_mov_b32_e32 v14, v1
	v_mov_b32_e32 v15, v1
	v_sub_u32_e32 v159, v126, v2
	v_sub_u32_e32 v161, 0, v0
	v_mov_b32_e32 v0, v1
	v_mov_b32_e32 v2, v1
	v_mov_b32_e32 v3, v1
	v_mov_b32_e32 v4, v1
	v_mov_b32_e32 v5, v1
	v_mov_b32_e32 v6, v1
	v_mov_b32_e32 v7, v1
	v_mov_b32_e32 v8, v1
	v_mov_b32_e32 v9, v1
	v_mov_b32_e32 v10, v1
	v_mov_b32_e32 v11, v1
	v_mov_b32_e32 v12, v1
	v_mov_b32_e32 v13, v1
	v_mov_b64_e32 v[30:31], v[14:15]
	v_mov_b64_e32 v[46:47], v[14:15]
	v_mul_u32_u24_e32 v156, 0x48, v116
	v_mov_b32_e32 v167, 0xf149f2ca
	v_mov_b32_e32 v169, 0
	v_mov_b64_e32 v[28:29], v[12:13]
	v_mov_b64_e32 v[26:27], v[10:11]
	v_mov_b64_e32 v[24:25], v[8:9]
	v_mov_b64_e32 v[22:23], v[6:7]
	v_mov_b64_e32 v[20:21], v[4:5]
	v_mov_b64_e32 v[18:19], v[2:3]
	v_mov_b64_e32 v[16:17], v[0:1]
	v_mov_b64_e32 v[44:45], v[12:13]
	v_mov_b64_e32 v[42:43], v[10:11]
	v_mov_b64_e32 v[40:41], v[8:9]
	v_mov_b64_e32 v[38:39], v[6:7]
	v_mov_b64_e32 v[36:37], v[4:5]
	v_mov_b64_e32 v[34:35], v[2:3]
	v_mov_b64_e32 v[32:33], v[0:1]
	v_lshrrev_b32_e32 v217, 1, v116
	v_xor_b32_e32 v217, v217, v116
	v_and_b32_e32 v217, 4, v217
	v_lshl_add_u32 v217, v217, 1, v217
	v_xor_b32_e32 v217, v217, v116
.LBB0_283:
	s_add_i32 s13, s12, 1
	s_min_i32 s4, s13, s10
	s_lshl_b32 s96, s4, 6
	v_add_u32_e32 v2, s96, v158
	v_add_u32_e32 v4, s96, v160
	v_ashrrev_i32_e32 v3, 31, v2
	v_ashrrev_i32_e32 v5, 31, v4
	v_lshlrev_b64 v[2:3], 7, v[2:3]
	v_lshlrev_b64 v[4:5], 7, v[4:5]
	v_lshl_add_u64 v[2:3], v[170:171], 0, v[2:3]
	v_lshl_add_u64 v[4:5], v[170:171], 0, v[4:5]
	s_lshl_b64 s[4:5], s[96:97], 1
	global_load_dwordx4 v[8:11], v[2:3], off
	s_nop 0
	global_load_dwordx4 v[4:7], v[4:5], off
	v_lshl_add_u64 v[2:3], v[162:163], 0, s[4:5]
	v_lshl_add_u64 v[48:49], v[164:165], 0, s[4:5]
	global_load_dwordx4 v[12:15], v[2:3], off
	global_load_dwordx4 v[112:115], v[48:49], off
	s_and_b32 s14, s12, 1
	s_mul_i32 s4, s14, 0x4800
	v_lshrrev_b64 v[2:3], s12, v[128:129]
	s_lshl_b32 s15, s12, 6
	v_and_b32_e32 v0, 1, v2
	s_or_b32 s5, s15, 63
	v_or_b32_e32 v3, s4, v131
	v_cmp_eq_u64_e64 s[38:39], 0, v[0:1]
	s_cmp_gt_i32 s5, s8
	v_add_u32_e32 v172, v3, v161
	s_mov_b64 s[4:5], -1
	s_cbranch_scc1 .LBB0_289
	v_mad_u32_u24 v0, v217, s37, v3
	v_lshl_add_u32 v215, v156, 1, v3
	ds_read_b128 v[220:223], v0
	ds_read_b128 v[236:239], v0 offset:4608
	ds_read_b128 v[224:227], v0 offset:32
	ds_read_b128 v[240:243], v0 offset:4640
	ds_read_b128 v[228:231], v0 offset:64
	ds_read_b128 v[244:247], v0 offset:4672
	ds_read_b128 v[232:235], v0 offset:96
	ds_read_b128 v[248:251], v0 offset:4704
	ds_read_b128 v[64:67], v215 offset:9216
	ds_read_b128 v[68:71], v215 offset:13824
	ds_read_b128 v[72:75], v215 offset:9248
	ds_read_b128 v[76:79], v215 offset:13856
	s_waitcnt lgkmcnt(11)
	v_mfma_f32_32x32x16_bf16 v[80:95], v[220:223], v[96:99], 0
	s_waitcnt lgkmcnt(10)
	v_mfma_f32_32x32x16_bf16 v[48:63], v[236:239], v[96:99], 0
	s_waitcnt lgkmcnt(9)
	v_mfma_f32_32x32x16_bf16 v[80:95], v[224:227], v[100:103], v[80:95]
	s_waitcnt lgkmcnt(8)
	v_mfma_f32_32x32x16_bf16 v[48:63], v[240:243], v[100:103], v[48:63]
	s_waitcnt lgkmcnt(7)
	v_mfma_f32_32x32x16_bf16 v[80:95], v[228:231], v[104:107], v[80:95]
	s_waitcnt lgkmcnt(6)
	v_mfma_f32_32x32x16_bf16 v[48:63], v[244:247], v[104:107], v[48:63]
	s_waitcnt lgkmcnt(5)
	v_mfma_f32_32x32x16_bf16 v[80:95], v[232:235], v[108:111], v[80:95]
	s_waitcnt lgkmcnt(4)
	v_mfma_f32_32x32x16_bf16 v[48:63], v[248:251], v[108:111], v[48:63]
	ds_read_b128 v[220:223], v215 offset:9280
	ds_read_b128 v[224:227], v215 offset:13888
	ds_read_b128 v[228:231], v215 offset:9312
	ds_read_b128 v[232:235], v215 offset:13920
	s_nop 7
	v_max3_f32 v0, v80, v81, v82
	v_max3_f32 v2, v88, v89, v90
	v_max3_f32 v0, v0, v83, v84
	v_max3_f32 v2, v2, v91, v92
	v_max3_f32 v0, v0, v85, v86
	v_max3_f32 v2, v2, v93, v94
	v_max3_f32 v0, v0, v87, v95
	v_max_f32_e32 v0, v0, v2
	v_cndmask_b32_e64 v0, v0, v202, s[38:39]
	ds_bpermute_b32 v2, v119, v0
	s_waitcnt lgkmcnt(0)
	v_max3_f32 v173, v167, v0, v2
	v_sub_f32_e32 v0, v167, v173
	v_exp_f32_e32 v0, v0
	v_cmp_eq_f32_e32 vcc, v173, v167
	s_cmp_eq_u64 vcc, exec
	s_cbranch_scc1 .Lnsw_keep0
	v_pk_mul_f32 v[46:47], v[46:47], v[0:1] op_sel_hi:[1,0]
	v_pk_mul_f32 v[44:45], v[44:45], v[0:1] op_sel_hi:[1,0]
	v_pk_mul_f32 v[42:43], v[42:43], v[0:1] op_sel_hi:[1,0]
	v_pk_mul_f32 v[40:41], v[40:41], v[0:1] op_sel_hi:[1,0]
	v_pk_mul_f32 v[38:39], v[38:39], v[0:1] op_sel_hi:[1,0]
	v_pk_mul_f32 v[36:37], v[36:37], v[0:1] op_sel_hi:[1,0]
	v_pk_mul_f32 v[34:35], v[34:35], v[0:1] op_sel_hi:[1,0]
	v_pk_mul_f32 v[32:33], v[32:33], v[0:1] op_sel_hi:[1,0]
	v_pk_mul_f32 v[30:31], v[30:31], v[0:1] op_sel_hi:[1,0]
	v_pk_mul_f32 v[28:29], v[28:29], v[0:1] op_sel_hi:[1,0]
	v_pk_mul_f32 v[26:27], v[26:27], v[0:1] op_sel_hi:[1,0]
	v_pk_mul_f32 v[24:25], v[24:25], v[0:1] op_sel_hi:[1,0]
	v_pk_mul_f32 v[22:23], v[22:23], v[0:1] op_sel_hi:[1,0]
	v_pk_mul_f32 v[20:21], v[20:21], v[0:1] op_sel_hi:[1,0]
	v_pk_mul_f32 v[18:19], v[18:19], v[0:1] op_sel_hi:[1,0]
	v_pk_mul_f32 v[16:17], v[16:17], v[0:1] op_sel_hi:[1,0]

.LBB0_299:
	v_mul_f32_e32 v0, 0xbfb8aa3b, v117
	v_exp_f32_e32 v0, v0
	s_lshl_b32 s4, s11, 18
	s_sub_i32 s5, 0xde1, s9
	s_max_i32 s12, s5, 0
	v_add_f32_e32 v0, 1.0, v0
	v_div_scale_f32 v3, s[6:7], v0, v0, 1.0
	v_rcp_f32_e32 v4, v3
	v_readlane_b32 s5, v253, 30
	v_fma_f32 v5, -v3, v4, 1.0
	v_fmac_f32_e32 v4, v5, v4
	v_div_scale_f32 v5, vcc, 1.0, v0, 1.0
	v_mul_f32_e32 v6, v5, v4
	v_fma_f32 v7, -v3, v6, v5
	v_fmac_f32_e32 v6, v7, v4
	v_fma_f32 v3, -v3, v6, v5
	v_div_fmas_f32 v3, v3, v4, v6
	v_div_fixup_f32 v0, v3, v0, 1.0
	ds_bpermute_b32 v3, v119, v2
	s_waitcnt lgkmcnt(0)
	v_add_f32_e32 v2, v2, v3
	v_div_scale_f32 v3, s[6:7], v2, v2, v0
	v_rcp_f32_e32 v4, v3
	s_lshl_b32 s6, s4, 1
	v_readlane_b32 s4, v253, 29
	s_add_u32 s4, s4, s6
	v_fma_f32 v5, -v3, v4, 1.0
	v_fmac_f32_e32 v4, v5, v4
	v_div_scale_f32 v5, vcc, v0, v2, v0
	v_mul_f32_e32 v6, v5, v4
	v_fma_f32 v7, -v3, v6, v5
	v_fmac_f32_e32 v6, v7, v4
	v_fma_f32 v3, -v3, v6, v5
	v_div_fmas_f32 v3, v3, v4, v6
	v_div_fixup_f32 v0, v3, v2, v0
	ds_read2st64_b32 v[2:3], v121 offset0:144 offset1:148
	ds_read2st64_b32 v[4:5], v121 offset0:208 offset1:212
	s_addc_u32 s5, s5, 0
	v_readlane_b32 s7, v253, 31
	s_add_u32 s6, s7, s6
	s_waitcnt lgkmcnt(1)
	v_fma_f32 v2, v64, v0, v2
	v_fmac_f32_e32 v3, v65, v0
	ds_write2st64_b32 v121, v2, v3 offset0:144 offset1:148
	ds_read2st64_b32 v[2:3], v121 offset0:152 offset1:156
	s_waitcnt lgkmcnt(2)
	v_fma_f32 v4, v48, v0, v4
	v_fmac_f32_e32 v5, v49, v0
	ds_write2st64_b32 v121, v4, v5 offset0:208 offset1:212
	ds_read2st64_b32 v[4:5], v121 offset0:216 offset1:220
	s_waitcnt lgkmcnt(2)
	v_fma_f32 v2, v66, v0, v2
	v_fmac_f32_e32 v3, v67, v0
	ds_write2st64_b32 v121, v2, v3 offset0:152 offset1:156
	ds_read2st64_b32 v[2:3], v121 offset0:160 offset1:164
	s_waitcnt lgkmcnt(2)
	v_fma_f32 v4, v50, v0, v4
	v_fmac_f32_e32 v5, v51, v0
	ds_write2st64_b32 v121, v4, v5 offset0:216 offset1:220
	ds_read2st64_b32 v[4:5], v121 offset0:224 offset1:228
	s_waitcnt lgkmcnt(2)
	v_fma_f32 v2, v68, v0, v2
	v_fmac_f32_e32 v3, v69, v0
	ds_write2st64_b32 v121, v2, v3 offset0:160 offset1:164
	ds_read2st64_b32 v[2:3], v121 offset0:168 offset1:172
	s_waitcnt lgkmcnt(2)
	v_fma_f32 v4, v52, v0, v4
	v_fmac_f32_e32 v5, v53, v0
	ds_write2st64_b32 v121, v4, v5 offset0:224 offset1:228
	ds_read2st64_b32 v[4:5], v121 offset0:232 offset1:236
	s_waitcnt lgkmcnt(2)
	v_fma_f32 v2, v70, v0, v2
	v_fmac_f32_e32 v3, v71, v0
	ds_write2st64_b32 v121, v2, v3 offset0:168 offset1:172
	ds_read2st64_b32 v[2:3], v121 offset0:176 offset1:180
	s_waitcnt lgkmcnt(2)
	v_fma_f32 v4, v54, v0, v4
	v_fmac_f32_e32 v5, v55, v0
	ds_write2st64_b32 v121, v4, v5 offset0:232 offset1:236
	ds_read2st64_b32 v[4:5], v121 offset0:240 offset1:244
	s_waitcnt lgkmcnt(2)
	v_fma_f32 v2, v72, v0, v2
	v_fmac_f32_e32 v3, v73, v0
	ds_write2st64_b32 v121, v2, v3 offset0:176 offset1:180
	ds_read2st64_b32 v[2:3], v121 offset0:184 offset1:188
	s_waitcnt lgkmcnt(2)
	v_fma_f32 v4, v56, v0, v4
	v_fmac_f32_e32 v5, v57, v0
	ds_write2st64_b32 v121, v4, v5 offset0:240 offset1:244
	ds_read2st64_b32 v[4:5], v121 offset0:248 offset1:252
	s_waitcnt lgkmcnt(2)
	v_fma_f32 v2, v74, v0, v2
	v_fmac_f32_e32 v3, v75, v0
	ds_write2st64_b32 v121, v2, v3 offset0:184 offset1:188
	ds_read2st64_b32 v[2:3], v121 offset0:192 offset1:196
	s_waitcnt lgkmcnt(2)
	v_fma_f32 v4, v58, v0, v4
	v_fmac_f32_e32 v5, v59, v0
	ds_write2st64_b32 v121, v4, v5 offset0:248 offset1:252
	ds_read_b32 v4, v125
	s_waitcnt lgkmcnt(2)
	v_fma_f32 v2, v76, v0, v2
	v_fmac_f32_e32 v3, v77, v0
	ds_write2st64_b32 v121, v2, v3 offset0:192 offset1:196
	ds_read_b32 v2, v127
	s_waitcnt lgkmcnt(2)
	v_fmac_f32_e32 v4, v60, v0
	ds_write_b32 v125, v4
	ds_read_b32 v4, v135
	v_readlane_b32 s7, v253, 32
	s_waitcnt lgkmcnt(2)
	v_fmac_f32_e32 v2, v61, v0
	ds_write_b32 v127, v2
	ds_read2st64_b32 v[2:3], v121 offset0:200 offset1:204
	v_mov_b32_e32 v6, v133
	s_addc_u32 s7, s7, 0
	s_lshr_b32 s11, s12, 6
	s_and_b32 s12, s12, 0x3ffffc0
	s_waitcnt lgkmcnt(0)
	v_fma_f32 v2, v78, v0, v2
	v_fmac_f32_e32 v3, v79, v0
	ds_write2st64_b32 v121, v2, v3 offset0:200 offset1:204
	ds_read_b32 v2, v152
	v_fmac_f32_e32 v4, v62, v0
	ds_write_b32 v135, v4
	s_lshl_b32 s96, s12, 1
	s_cmp_gt_i32 s11, s10
	s_waitcnt lgkmcnt(1)
	v_fmac_f32_e32 v2, v63, v0
	ds_write_b32 v152, v2
	s_nop 0
	v_ashrrev_i32_e32 v116, 3, v6
	v_add_u32_e32 v0, 0x100, v6
	v_add_u32_e32 v2, s12, v116
	v_ashrrev_i32_e32 v128, 3, v0
	v_ashrrev_i32_e32 v3, 31, v2
	v_lshlrev_b32_e32 v0, 3, v6
	v_lshlrev_b64 v[2:3], 7, v[2:3]
	v_and_b32_e32 v24, 56, v0
	v_lshl_add_u64 v[2:3], s[4:5], 0, v[2:3]
	v_lshlrev_b32_e32 v0, 1, v24
	v_lshl_add_u64 v[2:3], v[2:3], 0, v[0:1]
	global_load_dwordx4 v[8:11], v[2:3], off
	v_add_u32_e32 v2, s12, v128
	v_ashrrev_i32_e32 v3, 31, v2
	v_lshlrev_b64 v[2:3], 7, v[2:3]
	v_lshl_add_u64 v[2:3], s[4:5], 0, v[2:3]
	v_lshl_add_u64 v[2:3], v[2:3], 0, v[0:1]
	v_ashrrev_i32_e32 v117, 31, v116
	global_load_dwordx4 v[12:15], v[2:3], off
	v_lshlrev_b64 v[2:3], 13, v[116:117]
	v_lshl_add_u64 v[2:3], s[6:7], 0, v[2:3]
	v_lshl_add_u64 v[4:5], v[2:3], 0, s[96:97]
	v_lshl_add_u64 v[4:5], v[4:5], 0, v[0:1]
	v_ashrrev_i32_e32 v129, 31, v128
	global_load_dwordx4 v[16:19], v[4:5], off
	v_lshlrev_b64 v[4:5], 13, v[128:129]
	v_lshl_add_u64 v[4:5], s[6:7], 0, v[4:5]
	v_lshl_add_u64 v[20:21], v[4:5], 0, s[96:97]
	v_lshl_add_u64 v[20:21], v[20:21], 0, v[0:1]
	global_load_dwordx4 v[20:23], v[20:21], off
	v_mad_u64_u32 v[158:159], s[6:7], v116, s21, v[24:25]
	v_lshlrev_b32_e32 v7, 1, v158
	v_mad_u64_u32 v[160:161], s[6:7], v128, s21, v[24:25]
	s_waitcnt lgkmcnt(0)
	s_barrier
	s_waitcnt vmcnt(3)
	ds_write_b128 v7, v[8:11]
	v_lshlrev_b32_e32 v8, 1, v160
	s_waitcnt vmcnt(2)
	ds_write_b128 v8, v[12:15]
	s_waitcnt vmcnt(1)
	ds_write_b128 v7, v[16:19] offset:9216
	s_waitcnt vmcnt(0)
	ds_write_b128 v8, v[20:23] offset:9216
	s_waitcnt lgkmcnt(0)
	s_barrier
	s_cbranch_scc1 .LBB0_316
	v_lshl_add_u64 v[162:163], s[4:5], 0, v[0:1]
	v_lshl_add_u64 v[164:165], v[2:3], 0, v[0:1]
	v_lshl_add_u64 v[166:167], v[4:5], 0, v[0:1]
	v_bfe_u32 v0, v6, 5, 1
	v_lshlrev_b32_e32 v129, 4, v0
	v_lshlrev_b32_e32 v131, 2, v0
	v_lshlrev_b32_e32 v0, 3, v0
	v_mov_b32_e32 v14, v1
	v_mov_b32_e32 v15, v1
	v_and_b32_e32 v117, 31, v6
	v_sub_u32_e32 v161, 0, v0
	v_mov_b32_e32 v0, v1
	v_mov_b32_e32 v2, v1
	v_mov_b32_e32 v3, v1
	v_mov_b32_e32 v4, v1
	v_mov_b32_e32 v5, v1
	v_mov_b32_e32 v6, v1
	v_mov_b32_e32 v7, v1
	v_mov_b32_e32 v8, v1
	v_mov_b32_e32 v9, v1
	v_mov_b32_e32 v10, v1
	v_mov_b32_e32 v11, v1
	v_mov_b32_e32 v12, v1
	v_mov_b32_e32 v13, v1
	v_mov_b64_e32 v[30:31], v[14:15]
	v_mov_b64_e32 v[46:47], v[14:15]
	s_sub_i32 s9, 0xdff, s9
	v_add_u32_e32 v156, 0xfffffe00, v126
	v_mul_u32_u24_e32 v159, 0x48, v117
	v_mov_b32_e32 v168, 0xf149f2ca
	v_mov_b32_e32 v169, 0
	v_mov_b64_e32 v[28:29], v[12:13]
	v_mov_b64_e32 v[26:27], v[10:11]
	v_mov_b64_e32 v[24:25], v[8:9]
	v_mov_b64_e32 v[22:23], v[6:7]
	v_mov_b64_e32 v[20:21], v[4:5]
	v_mov_b64_e32 v[18:19], v[2:3]
	v_mov_b64_e32 v[16:17], v[0:1]
	v_mov_b64_e32 v[44:45], v[12:13]
	v_mov_b64_e32 v[42:43], v[10:11]
	v_mov_b64_e32 v[40:41], v[8:9]
	v_mov_b64_e32 v[38:39], v[6:7]
	v_mov_b64_e32 v[36:37], v[4:5]
	v_mov_b64_e32 v[34:35], v[2:3]
	v_mov_b64_e32 v[32:33], v[0:1]
	s_mov_b32 s12, s11
	v_lshrrev_b32_e32 v218, 1, v117
	v_xor_b32_e32 v218, v218, v117
	v_and_b32_e32 v218, 4, v218
	v_lshl_add_u32 v218, v218, 1, v218
	v_xor_b32_e32 v218, v218, v117

.LBB0_307:
	s_and_b64 vcc, exec, s[4:5]
	s_cbranch_vccz .Lnsw1_edgeback
	v_mad_u32_u24 v0, v218, s37, v14
	v_lshl_add_u32 v215, v159, 1, v14
	ds_read_b128 v[220:223], v0
	ds_read_b128 v[236:239], v0 offset:4608
	ds_read_b128 v[224:227], v0 offset:32
	ds_read_b128 v[240:243], v0 offset:4640
	ds_read_b128 v[228:231], v0 offset:64
	ds_read_b128 v[244:247], v0 offset:4672
	ds_read_b128 v[232:235], v0 offset:96
	ds_read_b128 v[248:251], v0 offset:4704
	ds_read_b128 v[64:67], v215 offset:9216
	ds_read_b128 v[68:71], v215 offset:13824
	ds_read_b128 v[72:75], v215 offset:9248
	ds_read_b128 v[76:79], v215 offset:13856
	s_waitcnt lgkmcnt(11)
	v_mfma_f32_32x32x16_bf16 v[80:95], v[220:223], v[96:99], 0
	s_waitcnt lgkmcnt(10)
	v_mfma_f32_32x32x16_bf16 v[48:63], v[236:239], v[96:99], 0
	s_waitcnt lgkmcnt(9)
	v_mfma_f32_32x32x16_bf16 v[80:95], v[224:227], v[100:103], v[80:95]
	s_waitcnt lgkmcnt(8)
	v_mfma_f32_32x32x16_bf16 v[48:63], v[240:243], v[100:103], v[48:63]
	s_waitcnt lgkmcnt(7)
	v_mfma_f32_32x32x16_bf16 v[80:95], v[228:231], v[104:107], v[80:95]
	s_waitcnt lgkmcnt(6)
	v_mfma_f32_32x32x16_bf16 v[48:63], v[244:247], v[104:107], v[48:63]
	s_waitcnt lgkmcnt(5)
	v_mfma_f32_32x32x16_bf16 v[80:95], v[232:235], v[108:111], v[80:95]
	s_waitcnt lgkmcnt(4)
	v_mfma_f32_32x32x16_bf16 v[48:63], v[248:251], v[108:111], v[48:63]
	ds_read_b128 v[220:223], v215 offset:9280
	ds_read_b128 v[224:227], v215 offset:13888
	ds_read_b128 v[228:231], v215 offset:9312
	ds_read_b128 v[232:235], v215 offset:13920
	s_nop 7
	v_max3_f32 v0, v80, v81, v82
	v_max3_f32 v216, v88, v89, v90
	v_max3_f32 v0, v0, v83, v84
	v_max3_f32 v216, v216, v91, v92
	v_max3_f32 v0, v0, v85, v86
	v_max3_f32 v216, v216, v93, v94
	v_max3_f32 v0, v0, v87, v95
	v_max_f32_e32 v0, v0, v216
	ds_bpermute_b32 v216, v119, v0
	s_waitcnt lgkmcnt(0)
	v_max3_f32 v173, v168, v0, v216
	v_sub_f32_e32 v0, v168, v173
	v_exp_f32_e32 v0, v0
	v_cmp_eq_f32_e32 vcc, v173, v168
	s_cmp_eq_u64 vcc, exec
	s_cbranch_scc1 .Lnsw1_keep0
	v_pk_mul_f32 v[46:47], v[46:47], v[0:1] op_sel_hi:[1,0]
	v_pk_mul_f32 v[44:45], v[44:45], v[0:1] op_sel_hi:[1,0]
	v_pk_mul_f32 v[42:43], v[42:43], v[0:1] op_sel_hi:[1,0]
	v_pk_mul_f32 v[40:41], v[40:41], v[0:1] op_sel_hi:[1,0]
	v_pk_mul_f32 v[38:39], v[38:39], v[0:1] op_sel_hi:[1,0]
	v_pk_mul_f32 v[36:37], v[36:37], v[0:1] op_sel_hi:[1,0]
	v_pk_mul_f32 v[34:35], v[34:35], v[0:1] op_sel_hi:[1,0]
	v_pk_mul_f32 v[32:33], v[32:33], v[0:1] op_sel_hi:[1,0]
	v_pk_mul_f32 v[30:31], v[30:31], v[0:1] op_sel_hi:[1,0]
	v_pk_mul_f32 v[28:29], v[28:29], v[0:1] op_sel_hi:[1,0]
	v_pk_mul_f32 v[26:27], v[26:27], v[0:1] op_sel_hi:[1,0]
	v_pk_mul_f32 v[24:25], v[24:25], v[0:1] op_sel_hi:[1,0]
	v_pk_mul_f32 v[22:23], v[22:23], v[0:1] op_sel_hi:[1,0]
	v_pk_mul_f32 v[20:21], v[20:21], v[0:1] op_sel_hi:[1,0]
	v_pk_mul_f32 v[18:19], v[18:19], v[0:1] op_sel_hi:[1,0]
	v_pk_mul_f32 v[16:17], v[16:17], v[0:1] op_sel_hi:[1,0]
